# P8b epilogue: pp loads prefetched 8 deep via base+offset, sigmoid in place on accumulators, fewer VALU per step
# baseline (speedup 1.0000x reference)
.LBB0_725:
	s_andn2_b64 vcc, exec, s[0:1]
	s_mov_b64 s[0:1], -1
	v_lshl_add_u32 v218, s34, 8, v189
	v_lshl_or_b32 v219, s57, 8, v190
	v_lshl_add_u32 v218, v218, 11, v219
	v_lshlrev_b32_e32 v210, 1, v218
	v_add_u32_e32 v211, 0x10000, v210
	v_add_u32_e32 v212, 0x20000, v210
	v_add_u32_e32 v213, 0x30000, v210
	v_add_u32_e32 v214, 0x80000, v210
	v_add_u32_e32 v215, 0x90000, v210
	v_add_u32_e32 v216, 0xa0000, v210
	v_add_u32_e32 v217, 0xb0000, v210
	global_load_dwordx4 v[2:5], v210, s[6:7] offset:0
	global_load_dwordx4 v[6:9], v210, s[6:7] offset:256
	global_load_dwordx4 v[10:13], v211, s[6:7] offset:0
	global_load_dwordx4 v[14:17], v211, s[6:7] offset:256
	global_load_dwordx4 v[18:21], v212, s[6:7] offset:0
	global_load_dwordx4 v[22:25], v212, s[6:7] offset:256
	global_load_dwordx4 v[26:29], v213, s[6:7] offset:0
	global_load_dwordx4 v[30:33], v213, s[6:7] offset:256
	v_mov_b32_e32 v206, 1.0
	v_mov_b32_e32 v207, 1.0
	v_mov_b32_e32 v208, 0xbfb8aa3b
	v_mul_f32_e32 v208, s12, v208
	v_mov_b32_e32 v209, v208
	v_pk_mul_f32 v[158:159], v[158:159], v[208:209]
	v_pk_mul_f32 v[160:161], v[160:161], v[208:209]
	v_pk_mul_f32 v[154:155], v[154:155], v[208:209]
	v_pk_mul_f32 v[156:157], v[156:157], v[208:209]
	v_exp_f32_e32 v158, v158
	v_exp_f32_e32 v159, v159
	v_exp_f32_e32 v160, v160
	v_exp_f32_e32 v161, v161
	v_exp_f32_e32 v154, v154
	v_exp_f32_e32 v155, v155
	v_exp_f32_e32 v156, v156
	v_exp_f32_e32 v157, v157
	v_pk_add_f32 v[158:159], v[158:159], v[206:207]
	v_pk_add_f32 v[160:161], v[160:161], v[206:207]
	v_pk_add_f32 v[154:155], v[154:155], v[206:207]
	v_pk_add_f32 v[156:157], v[156:157], v[206:207]
	v_rcp_f32_e32 v158, v158
	v_rcp_f32_e32 v159, v159
	v_rcp_f32_e32 v160, v160
	v_rcp_f32_e32 v161, v161
	v_rcp_f32_e32 v154, v154
	v_rcp_f32_e32 v155, v155
	v_rcp_f32_e32 v156, v156
	v_rcp_f32_e32 v157, v157
	s_waitcnt vmcnt(7)
	v_lshlrev_b32_e32 v198, 16, v2
	v_and_b32_e32 v199, 0xffff0000, v2
	v_lshlrev_b32_e32 v200, 16, v3
	v_and_b32_e32 v201, 0xffff0000, v3
	v_lshlrev_b32_e32 v202, 16, v4
	v_and_b32_e32 v203, 0xffff0000, v4
	v_lshlrev_b32_e32 v204, 16, v5
	v_and_b32_e32 v205, 0xffff0000, v5
	v_pk_mul_f32 v[198:199], v[198:199], v[158:159]
	v_pk_mul_f32 v[200:201], v[200:201], v[160:161]
	v_pk_mul_f32 v[202:203], v[202:203], v[154:155]
	v_pk_mul_f32 v[204:205], v[204:205], v[156:157]
	v_cvt_pk_bf16_f32 v2, v198, v199
	v_cvt_pk_bf16_f32 v3, v200, v201
	v_cvt_pk_bf16_f32 v4, v202, v203
	v_cvt_pk_bf16_f32 v5, v204, v205
	global_store_dwordx4 v210, v[2:5], s[6:7] offset:0
	s_nop 1
	global_load_dwordx4 v[2:5], v214, s[6:7] offset:0
	v_pk_mul_f32 v[150:151], v[150:151], v[208:209]
	v_pk_mul_f32 v[152:153], v[152:153], v[208:209]
	v_pk_mul_f32 v[146:147], v[146:147], v[208:209]
	v_pk_mul_f32 v[148:149], v[148:149], v[208:209]
	v_exp_f32_e32 v150, v150
	v_exp_f32_e32 v151, v151
	v_exp_f32_e32 v152, v152
	v_exp_f32_e32 v153, v153
	v_exp_f32_e32 v146, v146
	v_exp_f32_e32 v147, v147
	v_exp_f32_e32 v148, v148
	v_exp_f32_e32 v149, v149
	v_pk_add_f32 v[150:151], v[150:151], v[206:207]
	v_pk_add_f32 v[152:153], v[152:153], v[206:207]
	v_pk_add_f32 v[146:147], v[146:147], v[206:207]
	v_pk_add_f32 v[148:149], v[148:149], v[206:207]
	v_rcp_f32_e32 v150, v150
	v_rcp_f32_e32 v151, v151
	v_rcp_f32_e32 v152, v152
	v_rcp_f32_e32 v153, v153
	v_rcp_f32_e32 v146, v146
	v_rcp_f32_e32 v147, v147
	v_rcp_f32_e32 v148, v148
	v_rcp_f32_e32 v149, v149
	s_waitcnt vmcnt(8)
	v_lshlrev_b32_e32 v198, 16, v6
	v_and_b32_e32 v199, 0xffff0000, v6
	v_lshlrev_b32_e32 v200, 16, v7
	v_and_b32_e32 v201, 0xffff0000, v7
	v_lshlrev_b32_e32 v202, 16, v8
	v_and_b32_e32 v203, 0xffff0000, v8
	v_lshlrev_b32_e32 v204, 16, v9
	v_and_b32_e32 v205, 0xffff0000, v9
	v_pk_mul_f32 v[198:199], v[198:199], v[150:151]
	v_pk_mul_f32 v[200:201], v[200:201], v[152:153]
	v_pk_mul_f32 v[202:203], v[202:203], v[146:147]
	v_pk_mul_f32 v[204:205], v[204:205], v[148:149]
	v_cvt_pk_bf16_f32 v6, v198, v199
	v_cvt_pk_bf16_f32 v7, v200, v201
	v_cvt_pk_bf16_f32 v8, v202, v203
	v_cvt_pk_bf16_f32 v9, v204, v205
	global_store_dwordx4 v210, v[6:9], s[6:7] offset:256
	s_nop 1
	global_load_dwordx4 v[6:9], v214, s[6:7] offset:256
	v_pk_mul_f32 v[142:143], v[142:143], v[208:209]
	v_pk_mul_f32 v[144:145], v[144:145], v[208:209]
	v_pk_mul_f32 v[138:139], v[138:139], v[208:209]
	v_pk_mul_f32 v[140:141], v[140:141], v[208:209]
	v_exp_f32_e32 v142, v142
	v_exp_f32_e32 v143, v143
	v_exp_f32_e32 v144, v144
	v_exp_f32_e32 v145, v145
	v_exp_f32_e32 v138, v138
	v_exp_f32_e32 v139, v139
	v_exp_f32_e32 v140, v140
	v_exp_f32_e32 v141, v141
	v_pk_add_f32 v[142:143], v[142:143], v[206:207]
	v_pk_add_f32 v[144:145], v[144:145], v[206:207]
	v_pk_add_f32 v[138:139], v[138:139], v[206:207]
	v_pk_add_f32 v[140:141], v[140:141], v[206:207]
	v_rcp_f32_e32 v142, v142
	v_rcp_f32_e32 v143, v143
	v_rcp_f32_e32 v144, v144
	v_rcp_f32_e32 v145, v145
	v_rcp_f32_e32 v138, v138
	v_rcp_f32_e32 v139, v139
	v_rcp_f32_e32 v140, v140
	v_rcp_f32_e32 v141, v141
	s_waitcnt vmcnt(9)
	v_lshlrev_b32_e32 v198, 16, v10
	v_and_b32_e32 v199, 0xffff0000, v10
	v_lshlrev_b32_e32 v200, 16, v11
	v_and_b32_e32 v201, 0xffff0000, v11
	v_lshlrev_b32_e32 v202, 16, v12
	v_and_b32_e32 v203, 0xffff0000, v12
	v_lshlrev_b32_e32 v204, 16, v13
	v_and_b32_e32 v205, 0xffff0000, v13
	v_pk_mul_f32 v[198:199], v[198:199], v[142:143]
	v_pk_mul_f32 v[200:201], v[200:201], v[144:145]
	v_pk_mul_f32 v[202:203], v[202:203], v[138:139]
	v_pk_mul_f32 v[204:205], v[204:205], v[140:141]
	v_cvt_pk_bf16_f32 v10, v198, v199
	v_cvt_pk_bf16_f32 v11, v200, v201
	v_cvt_pk_bf16_f32 v12, v202, v203
	v_cvt_pk_bf16_f32 v13, v204, v205
	global_store_dwordx4 v211, v[10:13], s[6:7] offset:0
	s_nop 1
	global_load_dwordx4 v[10:13], v215, s[6:7] offset:0
	v_pk_mul_f32 v[134:135], v[134:135], v[208:209]
	v_pk_mul_f32 v[136:137], v[136:137], v[208:209]
	v_pk_mul_f32 v[130:131], v[130:131], v[208:209]
	v_pk_mul_f32 v[132:133], v[132:133], v[208:209]
	v_exp_f32_e32 v134, v134
	v_exp_f32_e32 v135, v135
	v_exp_f32_e32 v136, v136
	v_exp_f32_e32 v137, v137
	v_exp_f32_e32 v130, v130
	v_exp_f32_e32 v131, v131
	v_exp_f32_e32 v132, v132
	v_exp_f32_e32 v133, v133
	v_pk_add_f32 v[134:135], v[134:135], v[206:207]
	v_pk_add_f32 v[136:137], v[136:137], v[206:207]
	v_pk_add_f32 v[130:131], v[130:131], v[206:207]
	v_pk_add_f32 v[132:133], v[132:133], v[206:207]
	v_rcp_f32_e32 v134, v134
	v_rcp_f32_e32 v135, v135
	v_rcp_f32_e32 v136, v136
	v_rcp_f32_e32 v137, v137
	v_rcp_f32_e32 v130, v130
	v_rcp_f32_e32 v131, v131
	v_rcp_f32_e32 v132, v132
	v_rcp_f32_e32 v133, v133
	s_waitcnt vmcnt(10)
	v_lshlrev_b32_e32 v198, 16, v14
	v_and_b32_e32 v199, 0xffff0000, v14
	v_lshlrev_b32_e32 v200, 16, v15
	v_and_b32_e32 v201, 0xffff0000, v15
	v_lshlrev_b32_e32 v202, 16, v16
	v_and_b32_e32 v203, 0xffff0000, v16
	v_lshlrev_b32_e32 v204, 16, v17
	v_and_b32_e32 v205, 0xffff0000, v17
	v_pk_mul_f32 v[198:199], v[198:199], v[134:135]
	v_pk_mul_f32 v[200:201], v[200:201], v[136:137]
	v_pk_mul_f32 v[202:203], v[202:203], v[130:131]
	v_pk_mul_f32 v[204:205], v[204:205], v[132:133]
	v_cvt_pk_bf16_f32 v14, v198, v199
	v_cvt_pk_bf16_f32 v15, v200, v201
	v_cvt_pk_bf16_f32 v16, v202, v203
	v_cvt_pk_bf16_f32 v17, v204, v205
	global_store_dwordx4 v211, v[14:17], s[6:7] offset:256
	s_nop 1
	global_load_dwordx4 v[14:17], v215, s[6:7] offset:256
	v_pk_mul_f32 v[126:127], v[126:127], v[208:209]
	v_pk_mul_f32 v[128:129], v[128:129], v[208:209]
	v_pk_mul_f32 v[122:123], v[122:123], v[208:209]
	v_pk_mul_f32 v[124:125], v[124:125], v[208:209]
	v_exp_f32_e32 v126, v126
	v_exp_f32_e32 v127, v127
	v_exp_f32_e32 v128, v128
	v_exp_f32_e32 v129, v129
	v_exp_f32_e32 v122, v122
	v_exp_f32_e32 v123, v123
	v_exp_f32_e32 v124, v124
	v_exp_f32_e32 v125, v125
	v_pk_add_f32 v[126:127], v[126:127], v[206:207]
	v_pk_add_f32 v[128:129], v[128:129], v[206:207]
	v_pk_add_f32 v[122:123], v[122:123], v[206:207]
	v_pk_add_f32 v[124:125], v[124:125], v[206:207]
	v_rcp_f32_e32 v126, v126
	v_rcp_f32_e32 v127, v127
	v_rcp_f32_e32 v128, v128
	v_rcp_f32_e32 v129, v129
	v_rcp_f32_e32 v122, v122
	v_rcp_f32_e32 v123, v123
	v_rcp_f32_e32 v124, v124
	v_rcp_f32_e32 v125, v125
	s_waitcnt vmcnt(11)
	v_lshlrev_b32_e32 v198, 16, v18
	v_and_b32_e32 v199, 0xffff0000, v18
	v_lshlrev_b32_e32 v200, 16, v19
	v_and_b32_e32 v201, 0xffff0000, v19
	v_lshlrev_b32_e32 v202, 16, v20
	v_and_b32_e32 v203, 0xffff0000, v20
	v_lshlrev_b32_e32 v204, 16, v21
	v_and_b32_e32 v205, 0xffff0000, v21
	v_pk_mul_f32 v[198:199], v[198:199], v[126:127]
	v_pk_mul_f32 v[200:201], v[200:201], v[128:129]
	v_pk_mul_f32 v[202:203], v[202:203], v[122:123]
	v_pk_mul_f32 v[204:205], v[204:205], v[124:125]
	v_cvt_pk_bf16_f32 v18, v198, v199
	v_cvt_pk_bf16_f32 v19, v200, v201
	v_cvt_pk_bf16_f32 v20, v202, v203
	v_cvt_pk_bf16_f32 v21, v204, v205
	global_store_dwordx4 v212, v[18:21], s[6:7] offset:0
	s_nop 1
	global_load_dwordx4 v[18:21], v216, s[6:7] offset:0
	v_pk_mul_f32 v[118:119], v[118:119], v[208:209]
	v_pk_mul_f32 v[120:121], v[120:121], v[208:209]
	v_pk_mul_f32 v[114:115], v[114:115], v[208:209]
	v_pk_mul_f32 v[116:117], v[116:117], v[208:209]
	v_exp_f32_e32 v118, v118
	v_exp_f32_e32 v119, v119
	v_exp_f32_e32 v120, v120
	v_exp_f32_e32 v121, v121
	v_exp_f32_e32 v114, v114
	v_exp_f32_e32 v115, v115
	v_exp_f32_e32 v116, v116
	v_exp_f32_e32 v117, v117
	v_pk_add_f32 v[118:119], v[118:119], v[206:207]
	v_pk_add_f32 v[120:121], v[120:121], v[206:207]
	v_pk_add_f32 v[114:115], v[114:115], v[206:207]
	v_pk_add_f32 v[116:117], v[116:117], v[206:207]
	v_rcp_f32_e32 v118, v118
	v_rcp_f32_e32 v119, v119
	v_rcp_f32_e32 v120, v120
	v_rcp_f32_e32 v121, v121
	v_rcp_f32_e32 v114, v114
	v_rcp_f32_e32 v115, v115
	v_rcp_f32_e32 v116, v116
	v_rcp_f32_e32 v117, v117
	s_waitcnt vmcnt(12)
	v_lshlrev_b32_e32 v198, 16, v22
	v_and_b32_e32 v199, 0xffff0000, v22
	v_lshlrev_b32_e32 v200, 16, v23
	v_and_b32_e32 v201, 0xffff0000, v23
	v_lshlrev_b32_e32 v202, 16, v24
	v_and_b32_e32 v203, 0xffff0000, v24
	v_lshlrev_b32_e32 v204, 16, v25
	v_and_b32_e32 v205, 0xffff0000, v25
	v_pk_mul_f32 v[198:199], v[198:199], v[118:119]
	v_pk_mul_f32 v[200:201], v[200:201], v[120:121]
	v_pk_mul_f32 v[202:203], v[202:203], v[114:115]
	v_pk_mul_f32 v[204:205], v[204:205], v[116:117]
	v_cvt_pk_bf16_f32 v22, v198, v199
	v_cvt_pk_bf16_f32 v23, v200, v201
	v_cvt_pk_bf16_f32 v24, v202, v203
	v_cvt_pk_bf16_f32 v25, v204, v205
	global_store_dwordx4 v212, v[22:25], s[6:7] offset:256
	s_nop 1
	global_load_dwordx4 v[22:25], v216, s[6:7] offset:256
	v_pk_mul_f32 v[110:111], v[110:111], v[208:209]
	v_pk_mul_f32 v[112:113], v[112:113], v[208:209]
	v_pk_mul_f32 v[106:107], v[106:107], v[208:209]
	v_pk_mul_f32 v[108:109], v[108:109], v[208:209]
	v_exp_f32_e32 v110, v110
	v_exp_f32_e32 v111, v111
	v_exp_f32_e32 v112, v112
	v_exp_f32_e32 v113, v113
	v_exp_f32_e32 v106, v106
	v_exp_f32_e32 v107, v107
	v_exp_f32_e32 v108, v108
	v_exp_f32_e32 v109, v109
	v_pk_add_f32 v[110:111], v[110:111], v[206:207]
	v_pk_add_f32 v[112:113], v[112:113], v[206:207]
	v_pk_add_f32 v[106:107], v[106:107], v[206:207]
	v_pk_add_f32 v[108:109], v[108:109], v[206:207]
	v_rcp_f32_e32 v110, v110
	v_rcp_f32_e32 v111, v111
	v_rcp_f32_e32 v112, v112
	v_rcp_f32_e32 v113, v113
	v_rcp_f32_e32 v106, v106
	v_rcp_f32_e32 v107, v107
	v_rcp_f32_e32 v108, v108
	v_rcp_f32_e32 v109, v109
	s_waitcnt vmcnt(13)
	v_lshlrev_b32_e32 v198, 16, v26
	v_and_b32_e32 v199, 0xffff0000, v26
	v_lshlrev_b32_e32 v200, 16, v27
	v_and_b32_e32 v201, 0xffff0000, v27
	v_lshlrev_b32_e32 v202, 16, v28
	v_and_b32_e32 v203, 0xffff0000, v28
	v_lshlrev_b32_e32 v204, 16, v29
	v_and_b32_e32 v205, 0xffff0000, v29
	v_pk_mul_f32 v[198:199], v[198:199], v[110:111]
	v_pk_mul_f32 v[200:201], v[200:201], v[112:113]
	v_pk_mul_f32 v[202:203], v[202:203], v[106:107]
	v_pk_mul_f32 v[204:205], v[204:205], v[108:109]
	v_cvt_pk_bf16_f32 v26, v198, v199
	v_cvt_pk_bf16_f32 v27, v200, v201
	v_cvt_pk_bf16_f32 v28, v202, v203
	v_cvt_pk_bf16_f32 v29, v204, v205
	global_store_dwordx4 v213, v[26:29], s[6:7] offset:0
	s_nop 1
	global_load_dwordx4 v[26:29], v217, s[6:7] offset:0
	v_pk_mul_f32 v[102:103], v[102:103], v[208:209]
	v_pk_mul_f32 v[104:105], v[104:105], v[208:209]
	v_pk_mul_f32 v[98:99], v[98:99], v[208:209]
	v_pk_mul_f32 v[100:101], v[100:101], v[208:209]
	v_exp_f32_e32 v102, v102
	v_exp_f32_e32 v103, v103
	v_exp_f32_e32 v104, v104
	v_exp_f32_e32 v105, v105
	v_exp_f32_e32 v98, v98
	v_exp_f32_e32 v99, v99
	v_exp_f32_e32 v100, v100
	v_exp_f32_e32 v101, v101
	v_pk_add_f32 v[102:103], v[102:103], v[206:207]
	v_pk_add_f32 v[104:105], v[104:105], v[206:207]
	v_pk_add_f32 v[98:99], v[98:99], v[206:207]
	v_pk_add_f32 v[100:101], v[100:101], v[206:207]
	v_rcp_f32_e32 v102, v102
	v_rcp_f32_e32 v103, v103
	v_rcp_f32_e32 v104, v104
	v_rcp_f32_e32 v105, v105
	v_rcp_f32_e32 v98, v98
	v_rcp_f32_e32 v99, v99
	v_rcp_f32_e32 v100, v100
	v_rcp_f32_e32 v101, v101
	s_waitcnt vmcnt(14)
	v_lshlrev_b32_e32 v198, 16, v30
	v_and_b32_e32 v199, 0xffff0000, v30
	v_lshlrev_b32_e32 v200, 16, v31
	v_and_b32_e32 v201, 0xffff0000, v31
	v_lshlrev_b32_e32 v202, 16, v32
	v_and_b32_e32 v203, 0xffff0000, v32
	v_lshlrev_b32_e32 v204, 16, v33
	v_and_b32_e32 v205, 0xffff0000, v33
	v_pk_mul_f32 v[198:199], v[198:199], v[102:103]
	v_pk_mul_f32 v[200:201], v[200:201], v[104:105]
	v_pk_mul_f32 v[202:203], v[202:203], v[98:99]
	v_pk_mul_f32 v[204:205], v[204:205], v[100:101]
	v_cvt_pk_bf16_f32 v30, v198, v199
	v_cvt_pk_bf16_f32 v31, v200, v201
	v_cvt_pk_bf16_f32 v32, v202, v203
	v_cvt_pk_bf16_f32 v33, v204, v205
	global_store_dwordx4 v213, v[30:33], s[6:7] offset:256
	s_nop 1
	global_load_dwordx4 v[30:33], v217, s[6:7] offset:256
	v_pk_mul_f32 v[94:95], v[94:95], v[208:209]
	v_pk_mul_f32 v[96:97], v[96:97], v[208:209]
	v_pk_mul_f32 v[90:91], v[90:91], v[208:209]
	v_pk_mul_f32 v[92:93], v[92:93], v[208:209]
	v_exp_f32_e32 v94, v94
	v_exp_f32_e32 v95, v95
	v_exp_f32_e32 v96, v96
	v_exp_f32_e32 v97, v97
	v_exp_f32_e32 v90, v90
	v_exp_f32_e32 v91, v91
	v_exp_f32_e32 v92, v92
	v_exp_f32_e32 v93, v93
	v_pk_add_f32 v[94:95], v[94:95], v[206:207]
	v_pk_add_f32 v[96:97], v[96:97], v[206:207]
	v_pk_add_f32 v[90:91], v[90:91], v[206:207]
	v_pk_add_f32 v[92:93], v[92:93], v[206:207]
	v_rcp_f32_e32 v94, v94
	v_rcp_f32_e32 v95, v95
	v_rcp_f32_e32 v96, v96
	v_rcp_f32_e32 v97, v97
	v_rcp_f32_e32 v90, v90
	v_rcp_f32_e32 v91, v91
	v_rcp_f32_e32 v92, v92
	v_rcp_f32_e32 v93, v93
	s_waitcnt vmcnt(14)
	v_lshlrev_b32_e32 v198, 16, v2
	v_and_b32_e32 v199, 0xffff0000, v2
	v_lshlrev_b32_e32 v200, 16, v3
	v_and_b32_e32 v201, 0xffff0000, v3
	v_lshlrev_b32_e32 v202, 16, v4
	v_and_b32_e32 v203, 0xffff0000, v4
	v_lshlrev_b32_e32 v204, 16, v5
	v_and_b32_e32 v205, 0xffff0000, v5
	v_pk_mul_f32 v[198:199], v[198:199], v[94:95]
	v_pk_mul_f32 v[200:201], v[200:201], v[96:97]
	v_pk_mul_f32 v[202:203], v[202:203], v[90:91]
	v_pk_mul_f32 v[204:205], v[204:205], v[92:93]
	v_cvt_pk_bf16_f32 v2, v198, v199
	v_cvt_pk_bf16_f32 v3, v200, v201
	v_cvt_pk_bf16_f32 v4, v202, v203
	v_cvt_pk_bf16_f32 v5, v204, v205
	global_store_dwordx4 v214, v[2:5], s[6:7] offset:0
	v_pk_mul_f32 v[86:87], v[86:87], v[208:209]
	v_pk_mul_f32 v[88:89], v[88:89], v[208:209]
	v_pk_mul_f32 v[82:83], v[82:83], v[208:209]
	v_pk_mul_f32 v[84:85], v[84:85], v[208:209]
	v_exp_f32_e32 v86, v86
	v_exp_f32_e32 v87, v87
	v_exp_f32_e32 v88, v88
	v_exp_f32_e32 v89, v89
	v_exp_f32_e32 v82, v82
	v_exp_f32_e32 v83, v83
	v_exp_f32_e32 v84, v84
	v_exp_f32_e32 v85, v85
	v_pk_add_f32 v[86:87], v[86:87], v[206:207]
	v_pk_add_f32 v[88:89], v[88:89], v[206:207]
	v_pk_add_f32 v[82:83], v[82:83], v[206:207]
	v_pk_add_f32 v[84:85], v[84:85], v[206:207]
	v_rcp_f32_e32 v86, v86
	v_rcp_f32_e32 v87, v87
	v_rcp_f32_e32 v88, v88
	v_rcp_f32_e32 v89, v89
	v_rcp_f32_e32 v82, v82
	v_rcp_f32_e32 v83, v83
	v_rcp_f32_e32 v84, v84
	v_rcp_f32_e32 v85, v85
	s_waitcnt vmcnt(13)
	v_lshlrev_b32_e32 v198, 16, v6
	v_and_b32_e32 v199, 0xffff0000, v6
	v_lshlrev_b32_e32 v200, 16, v7
	v_and_b32_e32 v201, 0xffff0000, v7
	v_lshlrev_b32_e32 v202, 16, v8
	v_and_b32_e32 v203, 0xffff0000, v8
	v_lshlrev_b32_e32 v204, 16, v9
	v_and_b32_e32 v205, 0xffff0000, v9
	v_pk_mul_f32 v[198:199], v[198:199], v[86:87]
	v_pk_mul_f32 v[200:201], v[200:201], v[88:89]
	v_pk_mul_f32 v[202:203], v[202:203], v[82:83]
	v_pk_mul_f32 v[204:205], v[204:205], v[84:85]
	v_cvt_pk_bf16_f32 v6, v198, v199
	v_cvt_pk_bf16_f32 v7, v200, v201
	v_cvt_pk_bf16_f32 v8, v202, v203
	v_cvt_pk_bf16_f32 v9, v204, v205
	global_store_dwordx4 v214, v[6:9], s[6:7] offset:256
	v_pk_mul_f32 v[78:79], v[78:79], v[208:209]
	v_pk_mul_f32 v[80:81], v[80:81], v[208:209]
	v_pk_mul_f32 v[74:75], v[74:75], v[208:209]
	v_pk_mul_f32 v[76:77], v[76:77], v[208:209]
	v_exp_f32_e32 v78, v78
	v_exp_f32_e32 v79, v79
	v_exp_f32_e32 v80, v80
	v_exp_f32_e32 v81, v81
	v_exp_f32_e32 v74, v74
	v_exp_f32_e32 v75, v75
	v_exp_f32_e32 v76, v76
	v_exp_f32_e32 v77, v77
	v_pk_add_f32 v[78:79], v[78:79], v[206:207]
	v_pk_add_f32 v[80:81], v[80:81], v[206:207]
	v_pk_add_f32 v[74:75], v[74:75], v[206:207]
	v_pk_add_f32 v[76:77], v[76:77], v[206:207]
	v_rcp_f32_e32 v78, v78
	v_rcp_f32_e32 v79, v79
	v_rcp_f32_e32 v80, v80
	v_rcp_f32_e32 v81, v81
	v_rcp_f32_e32 v74, v74
	v_rcp_f32_e32 v75, v75
	v_rcp_f32_e32 v76, v76
	v_rcp_f32_e32 v77, v77
	s_waitcnt vmcnt(12)
	v_lshlrev_b32_e32 v198, 16, v10
	v_and_b32_e32 v199, 0xffff0000, v10
	v_lshlrev_b32_e32 v200, 16, v11
	v_and_b32_e32 v201, 0xffff0000, v11
	v_lshlrev_b32_e32 v202, 16, v12
	v_and_b32_e32 v203, 0xffff0000, v12
	v_lshlrev_b32_e32 v204, 16, v13
	v_and_b32_e32 v205, 0xffff0000, v13
	v_pk_mul_f32 v[198:199], v[198:199], v[78:79]
	v_pk_mul_f32 v[200:201], v[200:201], v[80:81]
	v_pk_mul_f32 v[202:203], v[202:203], v[74:75]
	v_pk_mul_f32 v[204:205], v[204:205], v[76:77]
	v_cvt_pk_bf16_f32 v10, v198, v199
	v_cvt_pk_bf16_f32 v11, v200, v201
	v_cvt_pk_bf16_f32 v12, v202, v203
	v_cvt_pk_bf16_f32 v13, v204, v205
	global_store_dwordx4 v215, v[10:13], s[6:7] offset:0
	v_pk_mul_f32 v[70:71], v[70:71], v[208:209]
	v_pk_mul_f32 v[72:73], v[72:73], v[208:209]
	v_pk_mul_f32 v[66:67], v[66:67], v[208:209]
	v_pk_mul_f32 v[68:69], v[68:69], v[208:209]
	v_exp_f32_e32 v70, v70
	v_exp_f32_e32 v71, v71
	v_exp_f32_e32 v72, v72
	v_exp_f32_e32 v73, v73
	v_exp_f32_e32 v66, v66
	v_exp_f32_e32 v67, v67
	v_exp_f32_e32 v68, v68
	v_exp_f32_e32 v69, v69
	v_pk_add_f32 v[70:71], v[70:71], v[206:207]
	v_pk_add_f32 v[72:73], v[72:73], v[206:207]
	v_pk_add_f32 v[66:67], v[66:67], v[206:207]
	v_pk_add_f32 v[68:69], v[68:69], v[206:207]
	v_rcp_f32_e32 v70, v70
	v_rcp_f32_e32 v71, v71
	v_rcp_f32_e32 v72, v72
	v_rcp_f32_e32 v73, v73
	v_rcp_f32_e32 v66, v66
	v_rcp_f32_e32 v67, v67
	v_rcp_f32_e32 v68, v68
	v_rcp_f32_e32 v69, v69
	s_waitcnt vmcnt(11)
	v_lshlrev_b32_e32 v198, 16, v14
	v_and_b32_e32 v199, 0xffff0000, v14
	v_lshlrev_b32_e32 v200, 16, v15
	v_and_b32_e32 v201, 0xffff0000, v15
	v_lshlrev_b32_e32 v202, 16, v16
	v_and_b32_e32 v203, 0xffff0000, v16
	v_lshlrev_b32_e32 v204, 16, v17
	v_and_b32_e32 v205, 0xffff0000, v17
	v_pk_mul_f32 v[198:199], v[198:199], v[70:71]
	v_pk_mul_f32 v[200:201], v[200:201], v[72:73]
	v_pk_mul_f32 v[202:203], v[202:203], v[66:67]
	v_pk_mul_f32 v[204:205], v[204:205], v[68:69]
	v_cvt_pk_bf16_f32 v14, v198, v199
	v_cvt_pk_bf16_f32 v15, v200, v201
	v_cvt_pk_bf16_f32 v16, v202, v203
	v_cvt_pk_bf16_f32 v17, v204, v205
	global_store_dwordx4 v215, v[14:17], s[6:7] offset:256
	v_pk_mul_f32 v[62:63], v[62:63], v[208:209]
	v_pk_mul_f32 v[64:65], v[64:65], v[208:209]
	v_pk_mul_f32 v[58:59], v[58:59], v[208:209]
	v_pk_mul_f32 v[60:61], v[60:61], v[208:209]
	v_exp_f32_e32 v62, v62
	v_exp_f32_e32 v63, v63
	v_exp_f32_e32 v64, v64
	v_exp_f32_e32 v65, v65
	v_exp_f32_e32 v58, v58
	v_exp_f32_e32 v59, v59
	v_exp_f32_e32 v60, v60
	v_exp_f32_e32 v61, v61
	v_pk_add_f32 v[62:63], v[62:63], v[206:207]
	v_pk_add_f32 v[64:65], v[64:65], v[206:207]
	v_pk_add_f32 v[58:59], v[58:59], v[206:207]
	v_pk_add_f32 v[60:61], v[60:61], v[206:207]
	v_rcp_f32_e32 v62, v62
	v_rcp_f32_e32 v63, v63
	v_rcp_f32_e32 v64, v64
	v_rcp_f32_e32 v65, v65
	v_rcp_f32_e32 v58, v58
	v_rcp_f32_e32 v59, v59
	v_rcp_f32_e32 v60, v60
	v_rcp_f32_e32 v61, v61
	s_waitcnt vmcnt(10)
	v_lshlrev_b32_e32 v198, 16, v18
	v_and_b32_e32 v199, 0xffff0000, v18
	v_lshlrev_b32_e32 v200, 16, v19
	v_and_b32_e32 v201, 0xffff0000, v19
	v_lshlrev_b32_e32 v202, 16, v20
	v_and_b32_e32 v203, 0xffff0000, v20
	v_lshlrev_b32_e32 v204, 16, v21
	v_and_b32_e32 v205, 0xffff0000, v21
	v_pk_mul_f32 v[198:199], v[198:199], v[62:63]
	v_pk_mul_f32 v[200:201], v[200:201], v[64:65]
	v_pk_mul_f32 v[202:203], v[202:203], v[58:59]
	v_pk_mul_f32 v[204:205], v[204:205], v[60:61]
	v_cvt_pk_bf16_f32 v18, v198, v199
	v_cvt_pk_bf16_f32 v19, v200, v201
	v_cvt_pk_bf16_f32 v20, v202, v203
	v_cvt_pk_bf16_f32 v21, v204, v205
	global_store_dwordx4 v216, v[18:21], s[6:7] offset:0
	v_pk_mul_f32 v[54:55], v[54:55], v[208:209]
	v_pk_mul_f32 v[56:57], v[56:57], v[208:209]
	v_pk_mul_f32 v[50:51], v[50:51], v[208:209]
	v_pk_mul_f32 v[52:53], v[52:53], v[208:209]
	v_exp_f32_e32 v54, v54
	v_exp_f32_e32 v55, v55
	v_exp_f32_e32 v56, v56
	v_exp_f32_e32 v57, v57
	v_exp_f32_e32 v50, v50
	v_exp_f32_e32 v51, v51
	v_exp_f32_e32 v52, v52
	v_exp_f32_e32 v53, v53
	v_pk_add_f32 v[54:55], v[54:55], v[206:207]
	v_pk_add_f32 v[56:57], v[56:57], v[206:207]
	v_pk_add_f32 v[50:51], v[50:51], v[206:207]
	v_pk_add_f32 v[52:53], v[52:53], v[206:207]
	v_rcp_f32_e32 v54, v54
	v_rcp_f32_e32 v55, v55
	v_rcp_f32_e32 v56, v56
	v_rcp_f32_e32 v57, v57
	v_rcp_f32_e32 v50, v50
	v_rcp_f32_e32 v51, v51
	v_rcp_f32_e32 v52, v52
	v_rcp_f32_e32 v53, v53
	s_waitcnt vmcnt(9)
	v_lshlrev_b32_e32 v198, 16, v22
	v_and_b32_e32 v199, 0xffff0000, v22
	v_lshlrev_b32_e32 v200, 16, v23
	v_and_b32_e32 v201, 0xffff0000, v23
	v_lshlrev_b32_e32 v202, 16, v24
	v_and_b32_e32 v203, 0xffff0000, v24
	v_lshlrev_b32_e32 v204, 16, v25
	v_and_b32_e32 v205, 0xffff0000, v25
	v_pk_mul_f32 v[198:199], v[198:199], v[54:55]
	v_pk_mul_f32 v[200:201], v[200:201], v[56:57]
	v_pk_mul_f32 v[202:203], v[202:203], v[50:51]
	v_pk_mul_f32 v[204:205], v[204:205], v[52:53]
	v_cvt_pk_bf16_f32 v22, v198, v199
	v_cvt_pk_bf16_f32 v23, v200, v201
	v_cvt_pk_bf16_f32 v24, v202, v203
	v_cvt_pk_bf16_f32 v25, v204, v205
	global_store_dwordx4 v216, v[22:25], s[6:7] offset:256
	v_pk_mul_f32 v[46:47], v[46:47], v[208:209]
	v_pk_mul_f32 v[48:49], v[48:49], v[208:209]
	v_pk_mul_f32 v[42:43], v[42:43], v[208:209]
	v_pk_mul_f32 v[44:45], v[44:45], v[208:209]
	v_exp_f32_e32 v46, v46
	v_exp_f32_e32 v47, v47
	v_exp_f32_e32 v48, v48
	v_exp_f32_e32 v49, v49
	v_exp_f32_e32 v42, v42
	v_exp_f32_e32 v43, v43
	v_exp_f32_e32 v44, v44
	v_exp_f32_e32 v45, v45
	v_pk_add_f32 v[46:47], v[46:47], v[206:207]
	v_pk_add_f32 v[48:49], v[48:49], v[206:207]
	v_pk_add_f32 v[42:43], v[42:43], v[206:207]
	v_pk_add_f32 v[44:45], v[44:45], v[206:207]
	v_rcp_f32_e32 v46, v46
	v_rcp_f32_e32 v47, v47
	v_rcp_f32_e32 v48, v48
	v_rcp_f32_e32 v49, v49
	v_rcp_f32_e32 v42, v42
	v_rcp_f32_e32 v43, v43
	v_rcp_f32_e32 v44, v44
	v_rcp_f32_e32 v45, v45
	s_waitcnt vmcnt(8)
	v_lshlrev_b32_e32 v198, 16, v26
	v_and_b32_e32 v199, 0xffff0000, v26
	v_lshlrev_b32_e32 v200, 16, v27
	v_and_b32_e32 v201, 0xffff0000, v27
	v_lshlrev_b32_e32 v202, 16, v28
	v_and_b32_e32 v203, 0xffff0000, v28
	v_lshlrev_b32_e32 v204, 16, v29
	v_and_b32_e32 v205, 0xffff0000, v29
	v_pk_mul_f32 v[198:199], v[198:199], v[46:47]
	v_pk_mul_f32 v[200:201], v[200:201], v[48:49]
	v_pk_mul_f32 v[202:203], v[202:203], v[42:43]
	v_pk_mul_f32 v[204:205], v[204:205], v[44:45]
	v_cvt_pk_bf16_f32 v26, v198, v199
	v_cvt_pk_bf16_f32 v27, v200, v201
	v_cvt_pk_bf16_f32 v28, v202, v203
	v_cvt_pk_bf16_f32 v29, v204, v205
	global_store_dwordx4 v217, v[26:29], s[6:7] offset:0
	v_pk_mul_f32 v[38:39], v[38:39], v[208:209]
	v_pk_mul_f32 v[40:41], v[40:41], v[208:209]
	v_pk_mul_f32 v[34:35], v[34:35], v[208:209]
	v_pk_mul_f32 v[36:37], v[36:37], v[208:209]
	v_exp_f32_e32 v38, v38
	v_exp_f32_e32 v39, v39
	v_exp_f32_e32 v40, v40
	v_exp_f32_e32 v41, v41
	v_exp_f32_e32 v34, v34
	v_exp_f32_e32 v35, v35
	v_exp_f32_e32 v36, v36
	v_exp_f32_e32 v37, v37
	v_pk_add_f32 v[38:39], v[38:39], v[206:207]
	v_pk_add_f32 v[40:41], v[40:41], v[206:207]
	v_pk_add_f32 v[34:35], v[34:35], v[206:207]
	v_pk_add_f32 v[36:37], v[36:37], v[206:207]
	v_rcp_f32_e32 v38, v38
	v_rcp_f32_e32 v39, v39
	v_rcp_f32_e32 v40, v40
	v_rcp_f32_e32 v41, v41
	v_rcp_f32_e32 v34, v34
	v_rcp_f32_e32 v35, v35
	v_rcp_f32_e32 v36, v36
	v_rcp_f32_e32 v37, v37
	s_waitcnt vmcnt(7)
	v_lshlrev_b32_e32 v198, 16, v30
	v_and_b32_e32 v199, 0xffff0000, v30
	v_lshlrev_b32_e32 v200, 16, v31
	v_and_b32_e32 v201, 0xffff0000, v31
	v_lshlrev_b32_e32 v202, 16, v32
	v_and_b32_e32 v203, 0xffff0000, v32
	v_lshlrev_b32_e32 v204, 16, v33
	v_and_b32_e32 v205, 0xffff0000, v33
	v_pk_mul_f32 v[198:199], v[198:199], v[38:39]
	v_pk_mul_f32 v[200:201], v[200:201], v[40:41]
	v_pk_mul_f32 v[202:203], v[202:203], v[34:35]
	v_pk_mul_f32 v[204:205], v[204:205], v[36:37]
	v_cvt_pk_bf16_f32 v30, v198, v199
	v_cvt_pk_bf16_f32 v31, v200, v201
	v_cvt_pk_bf16_f32 v32, v202, v203
	v_cvt_pk_bf16_f32 v33, v204, v205
	global_store_dwordx4 v217, v[30:33], s[6:7] offset:256
	s_cbranch_vccnz .LBB0_714
	s_andn2_b64 vcc, exec, s[4:5]
	s_cbranch_vccnz .LBB0_713
	s_barrier
	s_branch .LBB0_713
